# mlA: gate tables of all items computed up front, one item per wave in parallel; wave 0 copies its item's values from an LDS slot per item
# speedup vs baseline: 1.0019x; 1.0019x over previous
.Lmla_tab_done:
	s_or_b64 exec, exec, s[2:3]
	s_waitcnt lgkmcnt(0)
	s_barrier
	v_readfirstlane_b32 s98, v28
	s_lshr_b32 s98, s98, 6
	s_mov_b32 s99, 0
.Lmla_g_loop:
	s_lshl_b32 s6, s99, 3
	s_add_u32 s6, s6, s98
	s_lshl_b32 s6, s6, 8
	s_add_u32 s6, s6, s82
	s_cmp_ge_u32 s6, 0x880
	s_cbranch_scc1 .Lmla_g_done
	s_mul_hi_i32 s7, s6, 0x78787879
	s_lshr_b32 s8, s7, 31
	s_ashr_i32 s7, s7, 5
	s_add_i32 s7, s7, s8
	s_mul_i32 s8, s7, 0x44
	s_sub_u32 s8, s6, s8
	s_and_b32 s12, s7, 1
	s_lshr_b32 s13, s7, 3
	s_cmp_lt_u32 s8, 4
	s_cselect_b32 s2, 3, 0x43
	s_cselect_b32 s3, 0, 4
	s_sub_u32 s3, s8, s3
	s_sub_u32 s2, s2, s8
	s_cmp_lg_u32 s12, 0
	s_cselect_b32 s2, s2, s3
	s_lshl_b32 s2, s2, 6
	s_lshl_b32 s3, s13, 8
	s_add_u32 s3, s3, 0x4000
	s_lshl_b32 s13, s13, 12
	s_cmp_lt_u32 s8, 4
	s_cselect_b32 s3, s3, s13
	s_add_u32 s2, s2, s3
	v_and_b32_e32 v5, 63, v28
	v_sub_u32_e32 v6, 63, v5
	s_cmp_lg_u32 s12, 0
	s_cselect_b64 vcc, -1, 0
	v_cndmask_b32_e32 v5, v5, v6, vcc
	v_add_u32_e32 v5, s2, v5
	s_movk_i32 s3, 0x3600
	v_mul_lo_u32 v5, v5, s3
	s_bfe_u32 s9, s7, 0x20001
	s_lshl_b32 s3, s12, 3
	s_add_u32 s3, s3, s9
	s_lshl_b32 s3, s3, 1
	s_add_u32 s3, s3, 0x7601d40
	s_add_u32 s2, s88, s3
	s_addc_u32 s3, s89, 0
	s_nop 1
	global_load_ushort v39, v5, s[2:3]
	global_load_ushort v38, v5, s[2:3] offset:8
	s_lshl_b32 s12, s12, 2
	s_or_b32 s9, s9, s12
	v_readlane_b32 s12, v254, 61
	s_nop 3
	s_or_b32 s9, s9, s12
	s_lshl_b32 s9, s9, 2
	s_add_u32 s9, s9, 0x22340
	v_mov_b32_e32 v0, s9
	ds_read_b32 v1, v0 offset:64
	ds_read_b32 v0, v0
	s_mov_b32 s7, 0xbfb8aa3b
	v_mov_b32_e32 v14, 0x7f800000
	s_mul_i32 s8, s6, 0x300
	s_add_u32 s8, s14, s8
	s_waitcnt vmcnt(0) lgkmcnt(0)
	v_lshlrev_b32_e32 v39, 16, v39
	v_lshlrev_b32_e32 v38, 16, v38
	v_add_f32_e32 v0, v39, v0
	v_add_f32_e32 v2, v38, v1
	v_mul_f32_e64 v3, |v2|, s7
	v_fma_f32 v4, |v2|, s7, -v3
	s_mov_b32 s7, 0xb2a5705f
	v_rndne_f32_e32 v5, v3
	v_fma_f32 v4, |v2|, s7, v4
	v_sub_f32_e32 v3, v3, v5
	v_add_f32_e32 v3, v3, v4
	v_exp_f32_e32 v3, v3
	v_cvt_i32_f32_e32 v4, v5
	s_mov_b32 s7, 0x42ce8ed0
	v_cmp_ngt_f32_e64 vcc, |v2|, s7
	s_mov_b32 s7, 0xc2b17218
	v_ldexp_f32 v3, v3, v4
	v_cndmask_b32_e32 v3, 0, v3, vcc
	v_cmp_nlt_f32_e64 vcc, |v2|, s7
	v_min_f32_e32 v1, 0, v2
	s_mov_b32 s7, 0x3f2aaaab
	v_cndmask_b32_e32 v2, v14, v3, vcc
	v_add_f32_e32 v3, 1.0, v2
	v_add_f32_e32 v4, -1.0, v3
	v_sub_f32_e32 v5, v4, v3
	v_add_f32_e32 v5, 1.0, v5
	v_sub_f32_e32 v4, v2, v4
	v_add_f32_e32 v6, v4, v5
	v_frexp_mant_f32_e32 v4, v3
	v_cmp_gt_f32_e32 vcc, s7, v4
	v_cvt_f64_f32_e32 v[4:5], v3
	v_frexp_exp_i32_f64_e32 v4, v[4:5]
	v_subbrev_co_u32_e32 v4, vcc, 0, v4, vcc
	v_sub_u32_e32 v5, 0, v4
	v_ldexp_f32 v3, v3, v5
	v_ldexp_f32 v5, v6, v5
	v_add_f32_e32 v6, -1.0, v3
	v_add_f32_e32 v7, 1.0, v6
	v_sub_f32_e32 v7, v3, v7
	v_add_f32_e32 v7, v5, v7
	v_add_f32_e32 v8, v6, v7
	v_sub_f32_e32 v6, v6, v8
	v_add_f32_e32 v6, v7, v6
	v_add_f32_e32 v7, 1.0, v3
	v_add_f32_e32 v9, -1.0, v7
	v_sub_f32_e32 v3, v3, v9
	v_add_f32_e32 v3, v5, v3
	v_add_f32_e32 v5, v7, v3
	v_sub_f32_e32 v7, v7, v5
	v_add_f32_e32 v3, v3, v7
	v_rcp_f32_e32 v7, v5
	v_cvt_f32_i32_e32 v4, v4
	s_mov_b32 s7, 0x3f317218
	v_mul_f32_e32 v9, v8, v7
	v_mul_f32_e32 v10, v5, v9
	v_fma_f32 v11, v9, v5, -v10
	v_fmac_f32_e32 v11, v9, v3
	v_add_f32_e32 v12, v10, v11
	v_sub_f32_e32 v13, v8, v12
	v_sub_f32_e32 v8, v8, v13
	v_sub_f32_e32 v10, v12, v10
	v_sub_f32_e32 v8, v8, v12
	v_add_f32_e32 v6, v6, v8
	v_sub_f32_e32 v8, v10, v11
	v_add_f32_e32 v6, v8, v6
	v_add_f32_e32 v8, v13, v6
	v_mul_f32_e32 v10, v7, v8
	v_mul_f32_e32 v11, v5, v10
	v_fma_f32 v5, v10, v5, -v11
	v_fmac_f32_e32 v5, v10, v3
	v_sub_f32_e32 v3, v13, v8
	v_add_f32_e32 v3, v6, v3
	v_add_f32_e32 v6, v11, v5
	v_sub_f32_e32 v12, v8, v6
	v_sub_f32_e32 v8, v8, v12
	v_sub_f32_e32 v11, v6, v11
	v_sub_f32_e32 v6, v8, v6
	v_add_f32_e32 v3, v3, v6
	v_sub_f32_e32 v5, v11, v5
	v_add_f32_e32 v3, v5, v3
	v_add_f32_e32 v5, v9, v10
	v_add_f32_e32 v3, v12, v3
	v_sub_f32_e32 v6, v5, v9
	v_mul_f32_e32 v3, v7, v3
	v_sub_f32_e32 v6, v10, v6
	v_add_f32_e32 v3, v6, v3
	v_mul_f32_e32 v9, 0x3f317218, v4
	v_add_f32_e32 v6, v5, v3
	v_fma_f32 v10, v4, s7, -v9
	v_mul_f32_e32 v7, v6, v6
	v_mov_b32_e32 v8, 0x3ecc95a3
	v_fmac_f32_e32 v10, 0xb102e308, v4
	v_sub_f32_e32 v4, v6, v5
	v_fmamk_f32 v8, v7, 0x3e9b6dac, v8
	v_sub_f32_e32 v3, v3, v4
	v_add_f32_e32 v4, v9, v10
	v_fmaak_f32 v8, v7, v8, 0x3f2aaada
	v_sub_f32_e32 v5, v4, v9
	v_ldexp_f32 v9, v6, 1
	v_mul_f32_e32 v6, v6, v7
	v_mul_f32_e32 v6, v6, v8
	v_add_f32_e32 v7, v9, v6
	v_sub_f32_e32 v8, v7, v9
	v_ldexp_f32 v3, v3, 1
	v_sub_f32_e32 v6, v6, v8
	v_add_f32_e32 v3, v3, v6
	v_add_f32_e32 v6, v7, v3
	v_sub_f32_e32 v7, v6, v7
	v_sub_f32_e32 v3, v3, v7
	v_add_f32_e32 v7, v4, v6
	v_sub_f32_e32 v8, v7, v4
	v_sub_f32_e32 v9, v7, v8
	v_sub_f32_e32 v5, v10, v5
	v_sub_f32_e32 v4, v4, v9
	v_sub_f32_e32 v6, v6, v8
	v_add_f32_e32 v4, v6, v4
	v_add_f32_e32 v6, v5, v3
	v_sub_f32_e32 v8, v6, v5
	v_sub_f32_e32 v9, v6, v8
	v_sub_f32_e32 v5, v5, v9
	v_sub_f32_e32 v3, v3, v8
	v_add_f32_e32 v4, v6, v4
	v_add_f32_e32 v3, v3, v5
	v_add_f32_e32 v5, v7, v4
	v_sub_f32_e32 v6, v5, v7
	v_sub_f32_e32 v4, v4, v6
	v_add_f32_e32 v3, v3, v4
	s_mov_b32 s7, 0x7f800000
	v_add_f32_e32 v3, v5, v3
	v_cmp_neq_f32_e32 vcc, s7, v2
	s_mov_b32 s7, 0x33800000
	s_nop 0
	v_cndmask_b32_e32 v3, v14, v3, vcc
	v_cmp_lt_f32_e64 vcc, |v2|, s7
	s_mul_hi_i32 s7, s6, 0x300
	s_addc_u32 s9, s15, s7
	v_cndmask_b32_e32 v2, v3, v2, vcc
	v_sub_f32_e32 v1, v1, v2
	v_mov_b32_e32 v2, v1
	s_nop 1
	v_add_f32_dpp v2, v2, v2 row_shr:1 row_mask:0xf bank_mask:0xf
	s_nop 1
	v_add_f32_dpp v2, v2, v2 row_shr:2 row_mask:0xf bank_mask:0xf
	s_nop 1
	v_add_f32_dpp v2, v2, v2 row_shr:4 row_mask:0xf bank_mask:0xf
	s_nop 1
	v_add_f32_dpp v2, v2, v2 row_shr:8 row_mask:0xf bank_mask:0xf
	s_nop 1
	v_add_f32_dpp v2, v2, v2 row_bcast:15 row_mask:0xa bank_mask:0xf
	s_nop 1
	v_add_f32_dpp v2, v2, v2 row_bcast:31 row_mask:0xc bank_mask:0xf
	s_nop 1
	v_sub_f32_e32 v3, v0, v2
	v_mov_b32_e32 v4, v3
	s_nop 1
	v_max_f32_dpp v4, v4, v4 row_shr:1 row_mask:0xf bank_mask:0xf
	s_nop 1
	v_max_f32_dpp v4, v4, v4 row_shr:2 row_mask:0xf bank_mask:0xf
	s_nop 1
	v_max_f32_dpp v4, v4, v4 row_shr:4 row_mask:0xf bank_mask:0xf
	s_nop 1
	v_max_f32_dpp v4, v4, v4 row_shr:8 row_mask:0xf bank_mask:0xf
	s_nop 1
	v_max_f32_dpp v4, v4, v4 row_bcast:15 row_mask:0xa bank_mask:0xf
	s_nop 1
	v_max_f32_dpp v4, v4, v4 row_bcast:31 row_mask:0xc bank_mask:0xf
	s_nop 1
	v_lshl_add_u64 v[0:1], s[8:9], 0, v[112:113]
	global_store_dword v[0:1], v3, off
	global_store_dword v[0:1], v2, off offset:256
	global_store_dword v[0:1], v4, off offset:512
	v_readlane_b32 s8, v2, 63
	v_readlane_b32 s9, v4, 63
	s_lshl_b32 s10, s99, 3
	s_add_u32 s10, s10, s98
	s_lshl_b32 s2, s10, 8
	s_add_u32 s2, s2, 0x22400
	v_add_u32_e32 v5, s2, v42
	ds_write_b32 v5, v3
	s_mov_b64 s[2:3], exec
	s_and_b64 exec, exec, s[46:47]
	s_ashr_i32 s7, s6, 31
	s_lshl_b64 s[12:13], s[6:7], 3
	s_add_u32 s12, s16, s12
	s_addc_u32 s13, s17, s13
	s_lshl_b32 s10, s10, 2
	s_add_u32 s10, s10, 0x22d00
	v_mov_b32_e32 v1, s9
	v_mov_b32_e32 v0, s10
	ds_write_b32 v0, v1
	v_mov_b32_e32 v0, s8
	v_mov_b64_e32 v[2:3], s[12:13]
	global_store_dwordx2 v[2:3], v[0:1], off
	s_mov_b64 exec, s[2:3]
	s_add_u32 s99, s99, 1
	s_cmp_lt_u32 s99, 2
	s_cbranch_scc1 .Lmla_g_loop
.Lmla_g_done:
	s_waitcnt lgkmcnt(0)
	s_barrier
	s_mov_b32 s6, s82
	s_branch .LBB0_735

.LBB0_735:
	s_and_saveexec_b64 s[2:3], s[44:45]
	s_cbranch_execz .LBB0_738
	s_sub_u32 s7, s6, s82
	s_lshr_b32 s7, s7, 8
	s_lshl_b32 s8, s7, 8
	s_add_u32 s8, s8, 0x22400
	v_add_u32_e32 v0, s8, v42
	ds_read_b32 v3, v0
	s_lshl_b32 s8, s7, 2
	s_add_u32 s8, s8, 0x22d00
	v_mov_b32_e32 v1, s8
	ds_read_b32 v1, v1
	s_waitcnt lgkmcnt(0)
	ds_write_b32 v42, v3 offset:64512
	s_and_b64 exec, exec, s[46:47]
	s_cbranch_execz .LBB0_738
	v_readlane_b32 s7, v254, 33
	s_nop 3
	v_mov_b32_e32 v0, s7
	ds_write_b32 v0, v1
